# wave_sum in 7 norm loops + diff_combine: serial ds_bpermute butterfly replaced by DPP quad_perm/row_mirror adds and v_permlane16/32_swap (bit-identical sums)
# speedup vs baseline: 1.0068x; 1.0068x over previous
; __device__ __forceinline__ unsigned pk2(float lo, float hi) { f32x2_pk v = {lo, hi}; bf16x2_pk b = __builtin_convertvector(v, bf16x2_pk); return __builtin_bit_cast(unsigned, b); }
; __device__ __forceinline__ float wave_sum(float v) {
; #pragma unroll
;     for (int o = 1; o < 64; o <<= 1) v += __shfl_xor(v, o);
;     return v;
; }
; __device__ __forceinline__ void norm_phase(const float* xl, const float* xc, const float* g, const float* shift, const float* scale, bf16_t* Z, int row_lo, int nrows, int gw, int ngw, int lane) {
;     for (int m = row_lo + gw; m < nrows; m += ngw) {
;         const float* xr = m < ML ? xl + (size_t)m * D : xc + (size_t)(m - ML) * D; const int mr = m < ML ? (m >> 11) : 16;
;         f32x4 v[4]; float ss = 0.f;
; #pragma unroll
;         for (int j = 0; j < 4; ++j) { v[j] = *(const f32x4*)(xr + 4 * lane + 256 * j); ss += (v[j].x * v[j].x + v[j].y * v[j].y) + (v[j].z * v[j].z + v[j].w * v[j].w); }
;         const float ri = rsqrtf(wave_sum(ss) * (1.0f / D) + 1e-6f);
; #pragma unroll
;         for (int j = 0; j < 4; ++j) { const int c = 4 * lane + 256 * j; const f32x4 gv = *(const f32x4*)(g + c), sh = *(const f32x4*)(shift + (size_t)mr * 6144 + c), sc = *(const f32x4*)(scale + (size_t)mr * 6144 + c);
;             const f32x4 o = v[j] * ri * gv * (sc + 1.0f) + sh; u32x2 w; w.x = pk2(o.x, o.y); w.y = pk2(o.z, o.w); *(u32x2*)(Z + (size_t)m * D + c) = w; }
;     }
.LBB0_87:
	global_load_dwordx4 v[16:19], v14, s[14:15]
	global_load_dwordx4 v[20:23], v14, s[14:15] offset:1024
	global_load_dwordx4 v[24:27], v14, s[14:15] offset:3072
	global_load_dwordx4 v[28:31], v14, s[14:15] offset:2048
	s_min_i32 s1, s6, 0x8000
	s_ashr_i32 s1, s1, 11
	v_mad_i64_i32 v[44:45], s[2:3], s1, v212, v[4:5]
	global_load_dwordx4 v[32:35], v[44:45], off
	global_load_dwordx4 v[36:39], v[0:1], off
	v_mad_i64_i32 v[46:47], s[2:3], s1, v212, v[2:3]
	global_load_dwordx4 v[40:43], v[46:47], off
	s_lshl_b64 s[2:3], s[12:13], 11
	s_add_u32 s6, s6, s80
	s_addc_u32 s7, s7, s81
	s_add_u32 s10, s10, s48
	s_addc_u32 s11, s11, s49
	s_cmp_lt_i32 s6, 0x9000
	s_waitcnt vmcnt(0)
	v_pk_mul_f32 v[48:49], v[18:19], v[18:19]
	v_pk_mul_f32 v[50:51], v[16:17], v[16:17]
	s_waitcnt vmcnt(5)
	v_pk_mul_f32 v[52:53], v[22:23], v[22:23]
	v_pk_mul_f32 v[54:55], v[20:21], v[20:21]
	v_pk_mov_b32 v[60:61], v[50:51], v[48:49] op_sel:[1,0]
	v_mov_b32_e32 v51, v49
	v_pk_mov_b32 v[48:49], v[54:55], v[52:53] op_sel:[1,0]
	v_mov_b32_e32 v55, v53
	s_waitcnt vmcnt(4)
	v_mul_f32_e32 v59, v25, v25
	s_waitcnt vmcnt(3)
	v_mul_f32_e32 v56, v29, v29
	v_mul_f32_e32 v58, v31, v31
	v_pk_add_f32 v[50:51], v[60:61], v[50:51]
	v_pk_add_f32 v[48:49], v[48:49], v[54:55]
	v_mul_f32_e32 v15, v24, v24
	v_mul_f32_e32 v62, v26, v26
	v_mul_f32_e32 v63, v27, v27
	v_pk_fma_f32 v[52:53], v[28:29], v[28:29], v[56:57] op_sel_hi:[1,1,0]
	v_pk_fma_f32 v[56:57], v[30:31], v[30:31], v[58:59] op_sel_hi:[1,1,0]
	v_pk_add_f32 v[50:51], v[50:51], v[50:51] op_sel:[0,1] op_sel_hi:[1,0]
	v_pk_add_f32 v[48:49], v[48:49], v[48:49] op_sel:[0,1] op_sel_hi:[1,0]
	v_mov_b32_e32 v53, v62
	v_mov_b32_e32 v57, v63
	v_mov_b32_e32 v51, v15
	v_mov_b32_e32 v49, v59
	v_pk_add_f32 v[52:53], v[52:53], v[56:57]
	v_pk_add_f32 v[48:49], v[50:51], v[48:49]
	s_waitcnt vmcnt(2)
	v_pk_add_f32 v[34:35], v[34:35], 1.0 op_sel_hi:[1,0]
	v_pk_add_f32 v[48:49], v[48:49], v[52:53]
	v_pk_add_f32 v[32:33], v[32:33], 1.0 op_sel_hi:[1,0]
	v_add_f32_e32 v15, v48, v49
	s_nop 1
	v_add_f32_dpp v15, v15, v15 quad_perm:[1,0,3,2] row_mask:0xf bank_mask:0xf
	s_nop 1
	v_add_f32_dpp v15, v15, v15 quad_perm:[2,3,0,1] row_mask:0xf bank_mask:0xf
	s_nop 1
	v_add_f32_dpp v15, v15, v15 row_half_mirror row_mask:0xf bank_mask:0xf
	s_nop 1
	v_add_f32_dpp v15, v15, v15 row_mirror row_mask:0xf bank_mask:0xf
	v_mov_b32_e32 v48, v15
	s_nop 1
	v_permlane16_swap_b32_e32 v15, v48
	v_add_f32_e32 v15, v15, v48
	v_mov_b32_e32 v48, v15
	s_nop 1
	v_permlane32_swap_b32_e32 v15, v48
	v_add_f32_e32 v15, v15, v48
	s_waitcnt lgkmcnt(0)
	v_fmamk_f32 v15, v15, 0x3a800000, v199
	v_mul_f32_e32 v48, 0x4b800000, v15
	v_cmp_gt_f32_e32 vcc, s64, v15
	s_nop 1
	v_cndmask_b32_e32 v15, v15, v48, vcc
	v_rsq_f32_e32 v15, v15
	v_lshl_add_u64 v[48:49], v[6:7], 0, s[2:3]
	v_mul_f32_e32 v50, 0x45800000, v15
	v_cndmask_b32_e32 v50, v15, v50, vcc
	v_pk_mul_f32 v[18:19], v[18:19], v[50:51] op_sel_hi:[1,0]
	v_pk_mul_f32 v[16:17], v[16:17], v[50:51] op_sel_hi:[1,0]
	s_waitcnt vmcnt(1)
	v_pk_mul_f32 v[18:19], v[38:39], v[18:19]
	v_pk_mul_f32 v[16:17], v[36:37], v[16:17]
	s_waitcnt vmcnt(0)
	v_pk_fma_f32 v[18:19], v[34:35], v[18:19], v[42:43]
	v_pk_fma_f32 v[16:17], v[32:33], v[16:17], v[40:41]
	v_pk_mul_f32 v[22:23], v[22:23], v[50:51] op_sel_hi:[1,0]
	v_cvt_pk_bf16_f32 v16, v16, v17
	v_cvt_pk_bf16_f32 v17, v18, v19
	global_store_dwordx2 v[48:49], v[16:17], off
	global_load_dwordx4 v[16:19], v[0:1], off offset:1024
	s_nop 0
	global_load_dwordx4 v[32:35], v[44:45], off offset:1024
	global_load_dwordx4 v[36:39], v[46:47], off offset:1024
	v_pk_mul_f32 v[20:21], v[20:21], v[50:51] op_sel_hi:[1,0]
	v_pk_mul_f32 v[30:31], v[30:31], v[50:51] op_sel_hi:[1,0]
	v_pk_mul_f32 v[28:29], v[28:29], v[50:51] op_sel_hi:[1,0]
	v_pk_mul_f32 v[26:27], v[26:27], v[50:51] op_sel_hi:[1,0]
	v_pk_mul_f32 v[24:25], v[24:25], v[50:51] op_sel_hi:[1,0]
	s_waitcnt vmcnt(2)
	v_pk_mul_f32 v[16:17], v[16:17], v[20:21]
	v_pk_mul_f32 v[18:19], v[18:19], v[22:23]
	s_waitcnt vmcnt(1)
	v_pk_add_f32 v[20:21], v[34:35], 1.0 op_sel_hi:[1,0]
	v_pk_add_f32 v[22:23], v[32:33], 1.0 op_sel_hi:[1,0]
	s_waitcnt vmcnt(0)
	v_pk_fma_f32 v[18:19], v[20:21], v[18:19], v[38:39]
	v_pk_fma_f32 v[16:17], v[22:23], v[16:17], v[36:37]
	s_nop 0
	v_cvt_pk_bf16_f32 v16, v16, v17
	v_cvt_pk_bf16_f32 v17, v18, v19
	global_store_dwordx2 v[48:49], v[16:17], off offset:512
	global_load_dwordx4 v[16:19], v[0:1], off offset:2048
	s_nop 0
	global_load_dwordx4 v[20:23], v[44:45], off offset:2048
	global_load_dwordx4 v[32:35], v[46:47], off offset:2048
	s_waitcnt vmcnt(2)
	v_pk_mul_f32 v[16:17], v[16:17], v[28:29]
	v_pk_mul_f32 v[18:19], v[18:19], v[30:31]
	s_waitcnt vmcnt(1)
	v_pk_add_f32 v[22:23], v[22:23], 1.0 op_sel_hi:[1,0]
	v_pk_add_f32 v[20:21], v[20:21], 1.0 op_sel_hi:[1,0]
	s_waitcnt vmcnt(0)
	v_pk_fma_f32 v[18:19], v[22:23], v[18:19], v[34:35]
	v_pk_fma_f32 v[16:17], v[20:21], v[16:17], v[32:33]
	s_nop 0
	v_cvt_pk_bf16_f32 v16, v16, v17
	v_cvt_pk_bf16_f32 v17, v18, v19
	global_store_dwordx2 v[48:49], v[16:17], off offset:1024
	global_load_dwordx4 v[16:19], v[0:1], off offset:3072
	s_nop 0
	global_load_dwordx4 v[20:23], v[44:45], off offset:3072
	global_load_dwordx4 v[28:31], v[46:47], off offset:3072
	s_waitcnt vmcnt(2)
	v_pk_mul_f32 v[16:17], v[16:17], v[24:25]
	v_pk_mul_f32 v[18:19], v[18:19], v[26:27]
	s_waitcnt vmcnt(1)
	v_pk_add_f32 v[22:23], v[22:23], 1.0 op_sel_hi:[1,0]
	v_pk_add_f32 v[20:21], v[20:21], 1.0 op_sel_hi:[1,0]
	s_waitcnt vmcnt(0)
	v_pk_fma_f32 v[18:19], v[18:19], v[22:23], v[30:31]
	v_pk_fma_f32 v[16:17], v[16:17], v[20:21], v[28:29]
	s_nop 0
	v_cvt_pk_bf16_f32 v16, v16, v17
	v_cvt_pk_bf16_f32 v17, v18, v19
	global_store_dwordx2 v[48:49], v[16:17], off offset:1536
	s_cbranch_scc0 .LBB0_90

; __device__ __forceinline__ unsigned pk2(float lo, float hi) { f32x2_pk v = {lo, hi}; bf16x2_pk b = __builtin_convertvector(v, bf16x2_pk); return __builtin_bit_cast(unsigned, b); }
; __device__ __forceinline__ void diff_combine_phase(bf16_t* O0, const bf16_t* O1, const float* sg, float lamv, float post, int gw, int ngw, int lane) {
;     for (int m = gw; m < ML; m += ngw) { const size_t off = (size_t)m * D + 16 * lane; float v[16];
; #pragma unroll
;         for (int h = 0; h < 2; ++h) { const u32x4 a = *(const u32x4*)(O0 + off + 8 * h), bq = *(const u32x4*)(O1 + off + 8 * h);
;             v[8 * h + 0] = bflo(a.x) - lamv * bflo(bq.x); v[8 * h + 1] = bfhi(a.x) - lamv * bfhi(bq.x); v[8 * h + 2] = bflo(a.y) - lamv * bflo(bq.y); v[8 * h + 3] = bfhi(a.y) - lamv * bfhi(bq.y);
;             v[8 * h + 4] = bflo(a.z) - lamv * bflo(bq.z); v[8 * h + 5] = bfhi(a.z) - lamv * bfhi(bq.z); v[8 * h + 6] = bflo(a.w) - lamv * bflo(bq.w); v[8 * h + 7] = bfhi(a.w) - lamv * bfhi(bq.w); }
;         float ss = 0.f;
; #pragma unroll
;         for (int e = 0; e < 16; ++e) ss += v[e] * v[e];
;         ss += __shfl_xor(ss, 1); ss += __shfl_xor(ss, 2); ss += __shfl_xor(ss, 4);
;         const float ri = rsqrtf(ss * (1.0f / 128.0f) + 1e-6f) * post; const float* gp = sg + 16 * (lane & 7);
; #pragma unroll
;         for (int h = 0; h < 2; ++h) { u32x4 o; o.x = pk2(v[8 * h + 0] * ri * gp[8 * h + 0], v[8 * h + 1] * ri * gp[8 * h + 1]); o.y = pk2(v[8 * h + 2] * ri * gp[8 * h + 2], v[8 * h + 3] * ri * gp[8 * h + 3]);
;             o.z = pk2(v[8 * h + 4] * ri * gp[8 * h + 4], v[8 * h + 5] * ri * gp[8 * h + 5]); o.w = pk2(v[8 * h + 6] * ri * gp[8 * h + 6], v[8 * h + 7] * ri * gp[8 * h + 7]); *(u32x4*)(O0 + off + 8 * h) = o; } }
.LBB0_634:
	s_mov_b32 s2, 0xece00000
	s_mov_b32 s3, -1
	v_lshl_add_u64 v[18:19], v[4:5], 0, s[2:3]
	global_load_dwordx4 v[10:13], v[4:5], off offset:16
	global_load_dwordx4 v[14:17], v[4:5], off
	v_add_co_u32_e32 v22, vcc, 0xece00000, v4
	global_load_dwordx4 v[18:21], v[18:19], off offset:16
	s_nop 0
	v_addc_co_u32_e32 v23, vcc, -1, v5, vcc
	global_load_dwordx4 v[22:25], v[22:23], off
	s_nop 0
	global_load_dwordx4 v[26:29], v[2:3], off offset:16
	global_load_dwordx4 v[30:33], v[2:3], off
	v_add_u32_e32 v6, s80, v6
	s_waitcnt vmcnt(5)
	v_and_b32_e32 v34, 0xffff0000, v13
	v_lshlrev_b32_e32 v35, 16, v13
	s_waitcnt vmcnt(4)
	v_lshlrev_b32_e32 v36, 16, v17
	v_and_b32_e32 v37, 0xffff0000, v17
	v_lshlrev_b32_e32 v38, 16, v16
	v_and_b32_e32 v39, 0xffff0000, v16
	v_lshlrev_b32_e32 v16, 16, v15
	v_and_b32_e32 v17, 0xffff0000, v15
	v_lshlrev_b32_e32 v40, 16, v14
	v_and_b32_e32 v41, 0xffff0000, v14
	v_lshlrev_b32_e32 v14, 16, v12
	v_and_b32_e32 v15, 0xffff0000, v12
	v_lshlrev_b32_e32 v12, 16, v11
	v_and_b32_e32 v13, 0xffff0000, v11
	v_lshlrev_b32_e32 v42, 16, v10
	v_and_b32_e32 v43, 0xffff0000, v10
	s_waitcnt vmcnt(3)
	v_and_b32_e32 v10, 0xffff0000, v21
	v_lshlrev_b32_e32 v11, 16, v21
	v_lshlrev_b32_e32 v44, 16, v20
	v_and_b32_e32 v45, 0xffff0000, v20
	v_lshlrev_b32_e32 v20, 16, v19
	v_and_b32_e32 v21, 0xffff0000, v19
	v_lshlrev_b32_e32 v46, 16, v18
	v_and_b32_e32 v47, 0xffff0000, v18
	v_pk_fma_f32 v[18:19], v[0:1], v[10:11], v[34:35] neg_lo:[1,0,0] neg_hi:[1,0,0]
	v_pk_fma_f32 v[34:35], v[0:1], v[44:45], v[14:15] neg_lo:[1,0,0] neg_hi:[1,0,0]
	v_pk_fma_f32 v[20:21], v[0:1], v[20:21], v[12:13] neg_lo:[1,0,0] neg_hi:[1,0,0]
	s_waitcnt vmcnt(2)
	v_lshlrev_b32_e32 v10, 16, v25
	v_and_b32_e32 v11, 0xffff0000, v25
	v_lshlrev_b32_e32 v12, 16, v24
	v_and_b32_e32 v13, 0xffff0000, v24
	v_lshlrev_b32_e32 v14, 16, v23
	v_and_b32_e32 v15, 0xffff0000, v23
	v_lshlrev_b32_e32 v24, 16, v22
	v_and_b32_e32 v25, 0xffff0000, v22
	v_pk_fma_f32 v[14:15], v[0:1], v[14:15], v[16:17] neg_lo:[1,0,0] neg_hi:[1,0,0]
	v_pk_fma_f32 v[16:17], v[0:1], v[24:25], v[40:41] neg_lo:[1,0,0] neg_hi:[1,0,0]
	v_pk_fma_f32 v[12:13], v[0:1], v[12:13], v[38:39] neg_lo:[1,0,0] neg_hi:[1,0,0]
	v_pk_mul_f32 v[40:41], v[16:17], v[16:17]
	v_pk_mul_f32 v[38:39], v[14:15], v[14:15]
	v_add_f32_e32 v40, v40, v41
	v_add_f32_e32 v38, v38, v40
	v_pk_fma_f32 v[10:11], v[0:1], v[10:11], v[36:37] neg_lo:[1,0,0] neg_hi:[1,0,0]
	v_pk_mul_f32 v[36:37], v[12:13], v[12:13]
	v_add_f32_e32 v38, v39, v38
	v_add_f32_e32 v36, v36, v38
	v_pk_mul_f32 v[24:25], v[10:11], v[10:11]
	v_add_f32_e32 v36, v37, v36
	v_pk_fma_f32 v[42:43], v[0:1], v[46:47], v[42:43] neg_lo:[1,0,0] neg_hi:[1,0,0]
	v_add_f32_e32 v24, v24, v36
	v_pk_mul_f32 v[48:49], v[42:43], v[42:43]
	v_add_f32_e32 v24, v25, v24
	v_add_f32_e32 v24, v48, v24
	v_pk_mul_f32 v[46:47], v[20:21], v[20:21]
	v_add_f32_e32 v24, v49, v24
	v_add_f32_e32 v24, v46, v24
	v_pk_mul_f32 v[44:45], v[34:35], v[34:35]
	v_add_f32_e32 v24, v47, v24
	v_add_f32_e32 v24, v44, v24
	v_pk_mul_f32 v[22:23], v[18:19], v[18:19]
	v_add_f32_e32 v24, v45, v24
	v_add_f32_e32 v23, v23, v24
	v_add_f32_e32 v22, v22, v23
	s_nop 1
	v_add_f32_dpp v22, v22, v22 quad_perm:[1,0,3,2] row_mask:0xf bank_mask:0xf
	s_nop 1
	v_add_f32_dpp v22, v22, v22 quad_perm:[2,3,0,1] row_mask:0xf bank_mask:0xf
	s_nop 1
	v_add_f32_dpp v22, v22, v22 row_half_mirror row_mask:0xf bank_mask:0xf
	s_waitcnt lgkmcnt(0)
	v_fmamk_f32 v22, v22, 0x3c000000, v199
	v_mul_f32_e32 v23, 0x4b800000, v22
	v_cmp_gt_f32_e32 vcc, s64, v22
	s_nop 1
	v_cndmask_b32_e32 v22, v22, v23, vcc
	v_rsq_f32_e32 v22, v22
	s_nop 0
	v_mul_f32_e32 v23, 0x45800000, v22
	v_cndmask_b32_e32 v22, v22, v23, vcc
	v_mul_f32_e32 v22, 0x3ee34c56, v22
	v_pk_mul_f32 v[16:17], v[16:17], v[22:23] op_sel_hi:[1,0]
	v_pk_mul_f32 v[14:15], v[14:15], v[22:23] op_sel_hi:[1,0]
	v_pk_mul_f32 v[12:13], v[12:13], v[22:23] op_sel_hi:[1,0]
	v_pk_mul_f32 v[10:11], v[10:11], v[22:23] op_sel_hi:[1,0]
	s_waitcnt vmcnt(0)
	v_pk_mul_f32 v[16:17], v[30:31], v[16:17]
	v_pk_mul_f32 v[14:15], v[32:33], v[14:15]
	v_pk_mul_f32 v[12:13], v[26:27], v[12:13]
	v_pk_mul_f32 v[24:25], v[28:29], v[10:11]
	v_cvt_pk_bf16_f32 v10, v16, v17
	v_cvt_pk_bf16_f32 v11, v14, v15
	v_cvt_pk_bf16_f32 v12, v12, v13
	v_cvt_pk_bf16_f32 v13, v24, v25
	global_store_dwordx4 v[4:5], v[10:13], off
	global_load_dwordx4 v[10:13], v[2:3], off offset:32
	s_nop 0
	global_load_dwordx4 v[14:17], v[2:3], off offset:48
	v_pk_mul_f32 v[24:25], v[42:43], v[22:23] op_sel_hi:[1,0]
	v_pk_mul_f32 v[20:21], v[20:21], v[22:23] op_sel_hi:[1,0]
	v_pk_mul_f32 v[26:27], v[34:35], v[22:23] op_sel_hi:[1,0]
	v_pk_mul_f32 v[18:19], v[18:19], v[22:23] op_sel_hi:[1,0]
	v_cmp_lt_i32_e32 vcc, s10, v6
	s_and_b64 vcc, exec, vcc
	s_waitcnt vmcnt(1)
	v_pk_mul_f32 v[10:11], v[10:11], v[24:25]
	v_pk_mul_f32 v[12:13], v[12:13], v[20:21]
	s_waitcnt vmcnt(0)
	v_pk_mul_f32 v[14:15], v[14:15], v[26:27]
	v_pk_mul_f32 v[16:17], v[16:17], v[18:19] op_sel:[0,1] op_sel_hi:[1,0]
	v_cvt_pk_bf16_f32 v10, v10, v11
	v_cvt_pk_bf16_f32 v11, v12, v13
	v_cvt_pk_bf16_f32 v12, v14, v15
	v_cvt_pk_bf16_f32 v13, v16, v17
	global_store_dwordx4 v[4:5], v[10:13], off offset:16
	v_lshl_add_u64 v[4:5], v[4:5], 0, s[40:41]
	s_cbranch_vccz .LBB0_634

; __device__ __forceinline__ unsigned pk2(float lo, float hi) { f32x2_pk v = {lo, hi}; bf16x2_pk b = __builtin_convertvector(v, bf16x2_pk); return __builtin_bit_cast(unsigned, b); }
; __device__ __forceinline__ float wave_sum(float v) {
; #pragma unroll
;     for (int o = 1; o < 64; o <<= 1) v += __shfl_xor(v, o);
;     return v;
; }
; __device__ __forceinline__ void norm_phase(const float* xl, const float* xc, const float* g, const float* shift, const float* scale, bf16_t* Z, int row_lo, int nrows, int gw, int ngw, int lane) {
;     for (int m = row_lo + gw; m < nrows; m += ngw) {
;         const float* xr = m < ML ? xl + (size_t)m * D : xc + (size_t)(m - ML) * D; const int mr = m < ML ? (m >> 11) : 16;
;         f32x4 v[4]; float ss = 0.f;
; #pragma unroll
;         for (int j = 0; j < 4; ++j) { v[j] = *(const f32x4*)(xr + 4 * lane + 256 * j); ss += (v[j].x * v[j].x + v[j].y * v[j].y) + (v[j].z * v[j].z + v[j].w * v[j].w); }
;         const float ri = rsqrtf(wave_sum(ss) * (1.0f / D) + 1e-6f);
; #pragma unroll
;         for (int j = 0; j < 4; ++j) { const int c = 4 * lane + 256 * j; const f32x4 gv = *(const f32x4*)(g + c), sh = *(const f32x4*)(shift + (size_t)mr * 6144 + c), sc = *(const f32x4*)(scale + (size_t)mr * 6144 + c);
;             const f32x4 o = v[j] * ri * gv * (sc + 1.0f) + sh; u32x2 w; w.x = pk2(o.x, o.y); w.y = pk2(o.z, o.w); *(u32x2*)(Z + (size_t)m * D + c) = w; }
;     }
.LBB0_1653:
	global_load_dwordx4 v[12:15], v[24:25], off offset:-2048
	global_load_dwordx4 v[8:11], v[24:25], off offset:-1024
	s_addk_i32 s1, 0x600
	s_ashr_i32 s4, s1, 11
	s_cmpk_lt_i32 s1, 0x7a00
	s_waitcnt vmcnt(0)
	v_pk_mul_f32 v[0:1], v[14:15], v[14:15]
	v_pk_mul_f32 v[2:3], v[12:13], v[12:13]
	s_nop 0
	v_pk_mov_b32 v[4:5], v[2:3], v[0:1] op_sel:[1,0]
	v_mov_b32_e32 v3, v1
	v_pk_add_f32 v[28:29], v[4:5], v[2:3]
	v_pk_mul_f32 v[0:1], v[10:11], v[10:11]
	v_pk_mul_f32 v[2:3], v[8:9], v[8:9]
	v_pk_add_f32 v[28:29], v[28:29], v[28:29] op_sel:[0,1] op_sel_hi:[1,0]
	v_pk_mov_b32 v[4:5], v[2:3], v[0:1] op_sel:[1,0]
	v_mov_b32_e32 v3, v1
	v_pk_add_f32 v[30:31], v[4:5], v[2:3]
	global_load_dwordx4 v[0:3], v[24:25], off
	global_load_dwordx4 v[4:7], v[24:25], off offset:1024
	v_pk_add_f32 v[30:31], v[30:31], v[30:31] op_sel:[0,1] op_sel_hi:[1,0]
	v_lshl_add_u64 v[24:25], v[24:25], 0, s[60:61]
	s_waitcnt vmcnt(0)
	v_mul_f32_e32 v26, v4, v4
	v_mul_f32_e32 v37, v5, v5
	v_mov_b32_e32 v29, v26
	v_mov_b32_e32 v31, v37
	v_mul_f32_e32 v26, v1, v1
	v_mul_f32_e32 v38, v6, v6
	v_pk_add_f32 v[28:29], v[28:29], v[30:31]
	v_pk_fma_f32 v[30:31], v[0:1], v[0:1], v[26:27] op_sel_hi:[1,1,0]
	v_mul_f32_e32 v26, v3, v3
	v_mul_f32_e32 v40, v7, v7
	v_mov_b32_e32 v31, v38
	v_pk_fma_f32 v[38:39], v[2:3], v[2:3], v[26:27] op_sel_hi:[1,1,0]
	s_nop 0
	v_mov_b32_e32 v39, v40
	v_pk_add_f32 v[30:31], v[30:31], v[38:39]
	global_load_dwordx4 v[38:41], v[16:17], off
	v_pk_add_f32 v[28:29], v[28:29], v[30:31]
	v_mad_i64_i32 v[30:31], s[2:3], s4, v212, v[20:21]
	v_add_f32_e32 v26, v28, v29
	global_load_dwordx4 v[46:49], v[30:31], off
	s_nop 1
	v_add_f32_dpp v26, v26, v26 quad_perm:[1,0,3,2] row_mask:0xf bank_mask:0xf
	s_nop 1
	v_add_f32_dpp v26, v26, v26 quad_perm:[2,3,0,1] row_mask:0xf bank_mask:0xf
	s_nop 1
	v_add_f32_dpp v26, v26, v26 row_half_mirror row_mask:0xf bank_mask:0xf
	s_nop 1
	v_add_f32_dpp v26, v26, v26 row_mirror row_mask:0xf bank_mask:0xf
	v_mov_b32_e32 v28, v26
	s_nop 1
	v_permlane16_swap_b32_e32 v26, v28
	v_add_f32_e32 v26, v26, v28
	v_mov_b32_e32 v28, v26
	s_nop 1
	v_permlane32_swap_b32_e32 v26, v28
	v_add_f32_e32 v26, v26, v28
	s_waitcnt lgkmcnt(0)
	v_fmamk_f32 v26, v26, 0x3a800000, v199
	v_cmp_gt_f32_e32 vcc, s64, v26
	v_mul_f32_e32 v28, 0x4b800000, v26
	s_nop 0
	v_cndmask_b32_e32 v26, v26, v28, vcc
	v_rsq_f32_e32 v26, v26
	s_nop 0
	v_mul_f32_e32 v28, 0x45800000, v26
	v_cndmask_b32_e32 v26, v26, v28, vcc
	v_mad_i64_i32 v[28:29], s[2:3], s4, v212, v[18:19]
	global_load_dwordx4 v[42:45], v[28:29], off
	v_pk_mul_f32 v[14:15], v[14:15], v[26:27] op_sel_hi:[1,0]
	v_pk_mul_f32 v[12:13], v[12:13], v[26:27] op_sel_hi:[1,0]
	v_pk_mul_f32 v[10:11], v[10:11], v[26:27] op_sel_hi:[1,0]
	v_pk_mul_f32 v[8:9], v[8:9], v[26:27] op_sel_hi:[1,0]
	v_pk_mul_f32 v[2:3], v[2:3], v[26:27] op_sel_hi:[1,0]
	v_pk_mul_f32 v[0:1], v[0:1], v[26:27] op_sel_hi:[1,0]
	v_pk_mul_f32 v[6:7], v[6:7], v[26:27] op_sel_hi:[1,0]
	v_pk_mul_f32 v[4:5], v[4:5], v[26:27] op_sel_hi:[1,0]
	s_waitcnt vmcnt(2)
	v_pk_mul_f32 v[12:13], v[38:39], v[12:13]
	v_pk_mul_f32 v[14:15], v[40:41], v[14:15]
	s_waitcnt vmcnt(1)
	v_pk_add_f32 v[38:39], v[48:49], 1.0 op_sel_hi:[1,0]
	v_pk_add_f32 v[40:41], v[46:47], 1.0 op_sel_hi:[1,0]
	s_waitcnt vmcnt(0)
	v_pk_fma_f32 v[14:15], v[38:39], v[14:15], v[44:45]
	v_pk_fma_f32 v[12:13], v[40:41], v[12:13], v[42:43]
	s_nop 0
	v_cvt_pk_bf16_f32 v12, v12, v13
	v_cvt_pk_bf16_f32 v13, v14, v15
	global_store_dwordx2 v[22:23], v[12:13], off
	global_load_dwordx4 v[12:15], v[16:17], off offset:1024
	s_nop 0
	global_load_dwordx4 v[38:41], v[28:29], off offset:1024
	global_load_dwordx4 v[42:45], v[30:31], off offset:1024
	s_waitcnt vmcnt(2)
	v_pk_mul_f32 v[8:9], v[12:13], v[8:9]
	v_pk_mul_f32 v[10:11], v[14:15], v[10:11]
	s_waitcnt vmcnt(0)
	v_pk_add_f32 v[12:13], v[44:45], 1.0 op_sel_hi:[1,0]
	v_pk_add_f32 v[14:15], v[42:43], 1.0 op_sel_hi:[1,0]
	v_pk_fma_f32 v[10:11], v[12:13], v[10:11], v[40:41]
	v_pk_fma_f32 v[8:9], v[14:15], v[8:9], v[38:39]
	s_nop 0
	v_cvt_pk_bf16_f32 v8, v8, v9
	v_cvt_pk_bf16_f32 v9, v10, v11
	global_store_dwordx2 v[22:23], v[8:9], off offset:512
	global_load_dwordx4 v[8:11], v[16:17], off offset:2048
	s_nop 0
	global_load_dwordx4 v[12:15], v[28:29], off offset:2048
	global_load_dwordx4 v[38:41], v[30:31], off offset:2048
	s_waitcnt vmcnt(2)
	v_pk_mul_f32 v[0:1], v[8:9], v[0:1]
	v_pk_mul_f32 v[2:3], v[10:11], v[2:3]
	s_waitcnt vmcnt(0)
	v_pk_add_f32 v[8:9], v[40:41], 1.0 op_sel_hi:[1,0]
	v_pk_add_f32 v[10:11], v[38:39], 1.0 op_sel_hi:[1,0]
	v_pk_fma_f32 v[2:3], v[8:9], v[2:3], v[14:15]
	v_pk_fma_f32 v[0:1], v[10:11], v[0:1], v[12:13]
	s_nop 0
	v_cvt_pk_bf16_f32 v0, v0, v1
	v_cvt_pk_bf16_f32 v1, v2, v3
	global_store_dwordx2 v[22:23], v[0:1], off offset:1024
	global_load_dwordx4 v[0:3], v[16:17], off offset:3072
	s_nop 0
	global_load_dwordx4 v[8:11], v[28:29], off offset:3072
	global_load_dwordx4 v[12:15], v[30:31], off offset:3072
	s_waitcnt vmcnt(2)
	v_pk_mul_f32 v[0:1], v[0:1], v[4:5]
	v_pk_mul_f32 v[2:3], v[2:3], v[6:7]
	s_waitcnt vmcnt(0)
	v_pk_add_f32 v[4:5], v[14:15], 1.0 op_sel_hi:[1,0]
	v_pk_add_f32 v[6:7], v[12:13], 1.0 op_sel_hi:[1,0]
	v_pk_fma_f32 v[2:3], v[2:3], v[4:5], v[10:11]
	v_pk_fma_f32 v[0:1], v[0:1], v[6:7], v[8:9]
	s_nop 0
	v_cvt_pk_bf16_f32 v0, v0, v1
	v_cvt_pk_bf16_f32 v1, v2, v3
	global_store_dwordx2 v[22:23], v[0:1], off offset:1536
	v_lshl_add_u64 v[22:23], v[22:23], 0, s[58:59]
	s_cbranch_scc1 .LBB0_1653

; __device__ __forceinline__ unsigned pk2(float lo, float hi) { f32x2_pk v = {lo, hi}; bf16x2_pk b = __builtin_convertvector(v, bf16x2_pk); return __builtin_bit_cast(unsigned, b); }
; __device__ __forceinline__ float wave_sum(float v) {
; #pragma unroll
;     for (int o = 1; o < 64; o <<= 1) v += __shfl_xor(v, o);
;     return v;
; }
; __device__ __forceinline__ void norm_phase(const float* xl, const float* xc, const float* g, const float* shift, const float* scale, bf16_t* Z, int row_lo, int nrows, int gw, int ngw, int lane) {
;     for (int m = row_lo + gw; m < nrows; m += ngw) {
;         const float* xr = m < ML ? xl + (size_t)m * D : xc + (size_t)(m - ML) * D; const int mr = m < ML ? (m >> 11) : 16;
;         f32x4 v[4]; float ss = 0.f;
; #pragma unroll
;         for (int j = 0; j < 4; ++j) { v[j] = *(const f32x4*)(xr + 4 * lane + 256 * j); ss += (v[j].x * v[j].x + v[j].y * v[j].y) + (v[j].z * v[j].z + v[j].w * v[j].w); }
;         const float ri = rsqrtf(wave_sum(ss) * (1.0f / D) + 1e-6f);
; #pragma unroll
;         for (int j = 0; j < 4; ++j) { const int c = 4 * lane + 256 * j; const f32x4 gv = *(const f32x4*)(g + c), sh = *(const f32x4*)(shift + (size_t)mr * 6144 + c), sc = *(const f32x4*)(scale + (size_t)mr * 6144 + c);
;             const f32x4 o = v[j] * ri * gv * (sc + 1.0f) + sh; u32x2 w; w.x = pk2(o.x, o.y); w.y = pk2(o.z, o.w); *(u32x2*)(Z + (size_t)m * D + c) = w; }
;     }
.LBB0_1718:
	global_load_dwordx4 v[12:15], v36, s[20:21]
	global_load_dwordx4 v[8:11], v36, s[20:21] offset:1024
	s_min_i32 s3, s22, 0x8000
	s_ashr_i32 s3, s3, 11
	s_lshl_b64 s[18:19], s[18:19], 11
	s_add_i32 s86, s86, s80
	s_waitcnt vmcnt(0)
	v_pk_mul_f32 v[0:1], v[14:15], v[14:15]
	v_pk_mul_f32 v[2:3], v[12:13], v[12:13]
	s_nop 0
	v_pk_mov_b32 v[4:5], v[2:3], v[0:1] op_sel:[1,0]
	v_mov_b32_e32 v3, v1
	v_pk_add_f32 v[26:27], v[4:5], v[2:3]
	v_pk_mul_f32 v[0:1], v[10:11], v[10:11]
	v_pk_mul_f32 v[2:3], v[8:9], v[8:9]
	v_pk_add_f32 v[26:27], v[26:27], v[26:27] op_sel:[0,1] op_sel_hi:[1,0]
	v_pk_mov_b32 v[4:5], v[2:3], v[0:1] op_sel:[1,0]
	v_mov_b32_e32 v3, v1
	v_pk_add_f32 v[28:29], v[4:5], v[2:3]
	global_load_dwordx4 v[0:3], v36, s[20:21] offset:2048
	global_load_dwordx4 v[4:7], v36, s[20:21] offset:3072
	v_pk_add_f32 v[28:29], v[28:29], v[28:29] op_sel:[0,1] op_sel_hi:[1,0]
	s_waitcnt vmcnt(0)
	v_mul_f32_e32 v24, v4, v4
	v_mul_f32_e32 v37, v5, v5
	v_mov_b32_e32 v27, v24
	v_mov_b32_e32 v29, v37
	v_mul_f32_e32 v24, v1, v1
	v_mul_f32_e32 v38, v6, v6
	v_pk_add_f32 v[26:27], v[26:27], v[28:29]
	v_pk_fma_f32 v[28:29], v[0:1], v[0:1], v[24:25] op_sel_hi:[1,1,0]
	v_mul_f32_e32 v24, v3, v3
	v_mul_f32_e32 v40, v7, v7
	v_mov_b32_e32 v29, v38
	v_pk_fma_f32 v[38:39], v[2:3], v[2:3], v[24:25] op_sel_hi:[1,1,0]
	s_nop 0
	v_mov_b32_e32 v39, v40
	v_pk_add_f32 v[28:29], v[28:29], v[38:39]
	global_load_dwordx4 v[38:41], v[16:17], off
	v_pk_add_f32 v[26:27], v[26:27], v[28:29]
	v_mad_i64_i32 v[28:29], s[20:21], s3, v212, v[20:21]
	v_add_f32_e32 v24, v26, v27
	global_load_dwordx4 v[46:49], v[28:29], off
	s_nop 1
	v_add_f32_dpp v24, v24, v24 quad_perm:[1,0,3,2] row_mask:0xf bank_mask:0xf
	s_nop 1
	v_add_f32_dpp v24, v24, v24 quad_perm:[2,3,0,1] row_mask:0xf bank_mask:0xf
	s_nop 1
	v_add_f32_dpp v24, v24, v24 row_half_mirror row_mask:0xf bank_mask:0xf
	s_nop 1
	v_add_f32_dpp v24, v24, v24 row_mirror row_mask:0xf bank_mask:0xf
	v_mov_b32_e32 v26, v24
	s_nop 1
	v_permlane16_swap_b32_e32 v24, v26
	v_add_f32_e32 v24, v24, v26
	v_mov_b32_e32 v26, v24
	s_nop 1
	v_permlane32_swap_b32_e32 v24, v26
	v_add_f32_e32 v24, v24, v26
	s_waitcnt lgkmcnt(0)
	v_fmamk_f32 v24, v24, 0x3a800000, v199
	v_cmp_gt_f32_e32 vcc, s64, v24
	v_mul_f32_e32 v26, 0x4b800000, v24
	s_nop 0
	v_cndmask_b32_e32 v24, v24, v26, vcc
	v_rsq_f32_e32 v24, v24
	s_nop 0
	v_mul_f32_e32 v26, 0x45800000, v24
	v_cndmask_b32_e32 v24, v24, v26, vcc
	v_mad_i64_i32 v[26:27], s[20:21], s3, v212, v[18:19]
	global_load_dwordx4 v[42:45], v[26:27], off
	v_pk_mul_f32 v[14:15], v[14:15], v[24:25] op_sel_hi:[1,0]
	v_pk_mul_f32 v[12:13], v[12:13], v[24:25] op_sel_hi:[1,0]
	v_pk_mul_f32 v[10:11], v[10:11], v[24:25] op_sel_hi:[1,0]
	v_pk_mul_f32 v[8:9], v[8:9], v[24:25] op_sel_hi:[1,0]
	v_pk_mul_f32 v[2:3], v[2:3], v[24:25] op_sel_hi:[1,0]
	v_pk_mul_f32 v[0:1], v[0:1], v[24:25] op_sel_hi:[1,0]
	s_add_i32 s3, s86, 0x8000
	s_add_u32 s14, s14, s80
	v_pk_mul_f32 v[6:7], v[6:7], v[24:25] op_sel_hi:[1,0]
	v_pk_mul_f32 v[4:5], v[4:5], v[24:25] op_sel_hi:[1,0]
	s_addc_u32 s15, s15, s81
	s_waitcnt vmcnt(2)
	v_pk_mul_f32 v[12:13], v[38:39], v[12:13]
	v_pk_mul_f32 v[14:15], v[40:41], v[14:15]
	s_waitcnt vmcnt(1)
	v_pk_add_f32 v[38:39], v[48:49], 1.0 op_sel_hi:[1,0]
	v_pk_add_f32 v[40:41], v[46:47], 1.0 op_sel_hi:[1,0]
	v_lshl_add_u64 v[46:47], v[22:23], 0, s[18:19]
	v_readlane_b32 s18, v255, 27
	v_readlane_b32 s19, v255, 28
	s_add_u32 s16, s16, s18
	s_addc_u32 s17, s17, s19
	s_cmp_gt_i32 s3, 0x8fff
	s_waitcnt vmcnt(0)
	v_pk_fma_f32 v[14:15], v[38:39], v[14:15], v[44:45]
	v_pk_fma_f32 v[12:13], v[40:41], v[12:13], v[42:43]
	s_nop 0
	v_cvt_pk_bf16_f32 v12, v12, v13
	v_cvt_pk_bf16_f32 v13, v14, v15
	global_store_dwordx2 v[46:47], v[12:13], off
	global_load_dwordx4 v[12:15], v[16:17], off offset:1024
	s_nop 0
	global_load_dwordx4 v[38:41], v[26:27], off offset:1024
	global_load_dwordx4 v[42:45], v[28:29], off offset:1024
	s_waitcnt vmcnt(2)
	v_pk_mul_f32 v[8:9], v[12:13], v[8:9]
	v_pk_mul_f32 v[10:11], v[14:15], v[10:11]
	s_waitcnt vmcnt(0)
	v_pk_add_f32 v[12:13], v[44:45], 1.0 op_sel_hi:[1,0]
	v_pk_add_f32 v[14:15], v[42:43], 1.0 op_sel_hi:[1,0]
	v_pk_fma_f32 v[10:11], v[12:13], v[10:11], v[40:41]
	v_pk_fma_f32 v[8:9], v[14:15], v[8:9], v[38:39]
	s_nop 0
	v_cvt_pk_bf16_f32 v8, v8, v9
	v_cvt_pk_bf16_f32 v9, v10, v11
	global_store_dwordx2 v[46:47], v[8:9], off offset:512
	global_load_dwordx4 v[8:11], v[16:17], off offset:2048
	s_nop 0
	global_load_dwordx4 v[12:15], v[26:27], off offset:2048
	global_load_dwordx4 v[38:41], v[28:29], off offset:2048
	s_waitcnt vmcnt(2)
	v_pk_mul_f32 v[0:1], v[8:9], v[0:1]
	v_pk_mul_f32 v[2:3], v[10:11], v[2:3]
	s_waitcnt vmcnt(0)
	v_pk_add_f32 v[8:9], v[40:41], 1.0 op_sel_hi:[1,0]
	v_pk_add_f32 v[10:11], v[38:39], 1.0 op_sel_hi:[1,0]
	v_pk_fma_f32 v[2:3], v[8:9], v[2:3], v[14:15]
	v_pk_fma_f32 v[0:1], v[10:11], v[0:1], v[12:13]
	s_nop 0
	v_cvt_pk_bf16_f32 v0, v0, v1
	v_cvt_pk_bf16_f32 v1, v2, v3
	global_store_dwordx2 v[46:47], v[0:1], off offset:1024
	global_load_dwordx4 v[0:3], v[16:17], off offset:3072
	s_nop 0
	global_load_dwordx4 v[8:11], v[26:27], off offset:3072
	global_load_dwordx4 v[12:15], v[28:29], off offset:3072
	s_waitcnt vmcnt(2)
	v_pk_mul_f32 v[0:1], v[0:1], v[4:5]
	v_pk_mul_f32 v[2:3], v[2:3], v[6:7]
	s_waitcnt vmcnt(0)
	v_pk_add_f32 v[4:5], v[14:15], 1.0 op_sel_hi:[1,0]
	v_pk_add_f32 v[6:7], v[12:13], 1.0 op_sel_hi:[1,0]
	v_pk_fma_f32 v[2:3], v[2:3], v[4:5], v[10:11]
	v_pk_fma_f32 v[0:1], v[0:1], v[6:7], v[8:9]
	s_nop 0
	v_cvt_pk_bf16_f32 v0, v0, v1
	v_cvt_pk_bf16_f32 v1, v2, v3
	global_store_dwordx2 v[46:47], v[0:1], off offset:1536
	s_cbranch_scc1 .LBB0_1721

; __device__ __forceinline__ unsigned pk2(float lo, float hi) { f32x2_pk v = {lo, hi}; bf16x2_pk b = __builtin_convertvector(v, bf16x2_pk); return __builtin_bit_cast(unsigned, b); }
; __device__ __forceinline__ float wave_sum(float v) {
; #pragma unroll
;     for (int o = 1; o < 64; o <<= 1) v += __shfl_xor(v, o);
;     return v;
; }
; __device__ __forceinline__ void norm_phase(const float* xl, const float* xc, const float* g, const float* shift, const float* scale, bf16_t* Z, int row_lo, int nrows, int gw, int ngw, int lane) {
;     for (int m = row_lo + gw; m < nrows; m += ngw) {
;         const float* xr = m < ML ? xl + (size_t)m * D : xc + (size_t)(m - ML) * D; const int mr = m < ML ? (m >> 11) : 16;
;         f32x4 v[4]; float ss = 0.f;
; #pragma unroll
;         for (int j = 0; j < 4; ++j) { v[j] = *(const f32x4*)(xr + 4 * lane + 256 * j); ss += (v[j].x * v[j].x + v[j].y * v[j].y) + (v[j].z * v[j].z + v[j].w * v[j].w); }
;         const float ri = rsqrtf(wave_sum(ss) * (1.0f / D) + 1e-6f);
; #pragma unroll
;         for (int j = 0; j < 4; ++j) { const int c = 4 * lane + 256 * j; const f32x4 gv = *(const f32x4*)(g + c), sh = *(const f32x4*)(shift + (size_t)mr * 6144 + c), sc = *(const f32x4*)(scale + (size_t)mr * 6144 + c);
;             const f32x4 o = v[j] * ri * gv * (sc + 1.0f) + sh; u32x2 w; w.x = pk2(o.x, o.y); w.y = pk2(o.z, o.w); *(u32x2*)(Z + (size_t)m * D + c) = w; }
;     }
.LBB0_1725:
	global_load_dwordx4 v[12:15], v[30:31], off offset:-2048
	global_load_dwordx4 v[8:11], v[30:31], off offset:-1024
	s_ashr_i32 s1, s6, 11
	s_add_i32 s6, s6, s80
	s_cmpk_gt_i32 s6, 0x7fff
	s_waitcnt vmcnt(0)
	v_pk_mul_f32 v[0:1], v[14:15], v[14:15]
	v_pk_mul_f32 v[2:3], v[12:13], v[12:13]
	s_nop 0
	v_pk_mov_b32 v[4:5], v[2:3], v[0:1] op_sel:[1,0]
	v_mov_b32_e32 v3, v1
	v_pk_add_f32 v[34:35], v[4:5], v[2:3]
	v_pk_mul_f32 v[0:1], v[10:11], v[10:11]
	v_pk_mul_f32 v[2:3], v[8:9], v[8:9]
	v_pk_add_f32 v[34:35], v[34:35], v[34:35] op_sel:[0,1] op_sel_hi:[1,0]
	v_pk_mov_b32 v[4:5], v[2:3], v[0:1] op_sel:[1,0]
	v_mov_b32_e32 v3, v1
	v_pk_add_f32 v[36:37], v[4:5], v[2:3]
	global_load_dwordx4 v[0:3], v[30:31], off
	global_load_dwordx4 v[4:7], v[30:31], off offset:1024
	v_pk_add_f32 v[36:37], v[36:37], v[36:37] op_sel:[0,1] op_sel_hi:[1,0]
	v_lshl_add_u64 v[30:31], v[30:31], 0, s[8:9]
	s_waitcnt vmcnt(0)
	v_mul_f32_e32 v32, v4, v4
	v_mul_f32_e32 v43, v5, v5
	v_mov_b32_e32 v35, v32
	v_mov_b32_e32 v37, v43
	v_mul_f32_e32 v32, v1, v1
	v_mul_f32_e32 v44, v6, v6
	v_pk_add_f32 v[34:35], v[34:35], v[36:37]
	v_pk_fma_f32 v[36:37], v[0:1], v[0:1], v[32:33] op_sel_hi:[1,1,0]
	v_mul_f32_e32 v32, v3, v3
	v_mul_f32_e32 v46, v7, v7
	v_mov_b32_e32 v37, v44
	v_pk_fma_f32 v[44:45], v[2:3], v[2:3], v[32:33] op_sel_hi:[1,1,0]
	s_nop 0
	v_mov_b32_e32 v45, v46
	v_pk_add_f32 v[36:37], v[36:37], v[44:45]
	global_load_dwordx4 v[44:47], v[16:17], off
	v_pk_add_f32 v[34:35], v[34:35], v[36:37]
	v_mad_i64_i32 v[36:37], s[2:3], s1, v212, v[26:27]
	v_add_f32_e32 v32, v34, v35
	global_load_dwordx4 v[52:55], v[36:37], off
	s_nop 1
	v_add_f32_dpp v32, v32, v32 quad_perm:[1,0,3,2] row_mask:0xf bank_mask:0xf
	s_nop 1
	v_add_f32_dpp v32, v32, v32 quad_perm:[2,3,0,1] row_mask:0xf bank_mask:0xf
	s_nop 1
	v_add_f32_dpp v32, v32, v32 row_half_mirror row_mask:0xf bank_mask:0xf
	s_nop 1
	v_add_f32_dpp v32, v32, v32 row_mirror row_mask:0xf bank_mask:0xf
	v_mov_b32_e32 v34, v32
	s_nop 1
	v_permlane16_swap_b32_e32 v32, v34
	v_add_f32_e32 v32, v32, v34
	v_mov_b32_e32 v34, v32
	s_nop 1
	v_permlane32_swap_b32_e32 v32, v34
	v_add_f32_e32 v32, v32, v34
	s_waitcnt lgkmcnt(0)
	v_fmamk_f32 v32, v32, 0x3a800000, v199
	v_cmp_gt_f32_e32 vcc, s64, v32
	v_mul_f32_e32 v34, 0x4b800000, v32
	s_nop 0
	v_cndmask_b32_e32 v32, v32, v34, vcc
	v_rsq_f32_e32 v32, v32
	s_nop 0
	v_mul_f32_e32 v34, 0x45800000, v32
	v_cndmask_b32_e32 v32, v32, v34, vcc
	v_mad_i64_i32 v[34:35], s[2:3], s1, v212, v[24:25]
	global_load_dwordx4 v[48:51], v[34:35], off
	v_pk_mul_f32 v[14:15], v[14:15], v[32:33] op_sel_hi:[1,0]
	v_pk_mul_f32 v[12:13], v[12:13], v[32:33] op_sel_hi:[1,0]
	v_pk_mul_f32 v[10:11], v[10:11], v[32:33] op_sel_hi:[1,0]
	v_pk_mul_f32 v[8:9], v[8:9], v[32:33] op_sel_hi:[1,0]
	v_pk_mul_f32 v[2:3], v[2:3], v[32:33] op_sel_hi:[1,0]
	v_pk_mul_f32 v[0:1], v[0:1], v[32:33] op_sel_hi:[1,0]
	v_pk_mul_f32 v[6:7], v[6:7], v[32:33] op_sel_hi:[1,0]
	v_pk_mul_f32 v[4:5], v[4:5], v[32:33] op_sel_hi:[1,0]
	s_waitcnt vmcnt(2)
	v_pk_mul_f32 v[12:13], v[44:45], v[12:13]
	v_pk_mul_f32 v[14:15], v[46:47], v[14:15]
	s_waitcnt vmcnt(1)
	v_pk_add_f32 v[44:45], v[54:55], 1.0 op_sel_hi:[1,0]
	v_pk_add_f32 v[46:47], v[52:53], 1.0 op_sel_hi:[1,0]
	s_waitcnt vmcnt(0)
	v_pk_fma_f32 v[14:15], v[44:45], v[14:15], v[50:51]
	v_pk_fma_f32 v[12:13], v[46:47], v[12:13], v[48:49]
	s_nop 0
	v_cvt_pk_bf16_f32 v12, v12, v13
	v_cvt_pk_bf16_f32 v13, v14, v15
	global_store_dwordx2 v[28:29], v[12:13], off
	global_load_dwordx4 v[12:15], v[18:19], off
	s_nop 0
	global_load_dwordx4 v[44:47], v[34:35], off offset:1024
	global_load_dwordx4 v[48:51], v[36:37], off offset:1024
	s_waitcnt vmcnt(2)
	v_pk_mul_f32 v[8:9], v[12:13], v[8:9]
	v_pk_mul_f32 v[10:11], v[14:15], v[10:11]
	s_waitcnt vmcnt(0)
	v_pk_add_f32 v[12:13], v[50:51], 1.0 op_sel_hi:[1,0]
	v_pk_add_f32 v[14:15], v[48:49], 1.0 op_sel_hi:[1,0]
	v_pk_fma_f32 v[10:11], v[12:13], v[10:11], v[46:47]
	v_pk_fma_f32 v[8:9], v[14:15], v[8:9], v[44:45]
	s_nop 0
	v_cvt_pk_bf16_f32 v8, v8, v9
	v_cvt_pk_bf16_f32 v9, v10, v11
	global_store_dwordx2 v[28:29], v[8:9], off offset:512
	global_load_dwordx4 v[8:11], v[20:21], off
	s_nop 0
	global_load_dwordx4 v[12:15], v[34:35], off offset:2048
	global_load_dwordx4 v[44:47], v[36:37], off offset:2048
	s_waitcnt vmcnt(2)
	v_pk_mul_f32 v[0:1], v[8:9], v[0:1]
	v_pk_mul_f32 v[2:3], v[10:11], v[2:3]
	s_waitcnt vmcnt(0)
	v_pk_add_f32 v[8:9], v[46:47], 1.0 op_sel_hi:[1,0]
	v_pk_add_f32 v[10:11], v[44:45], 1.0 op_sel_hi:[1,0]
	v_pk_fma_f32 v[2:3], v[8:9], v[2:3], v[14:15]
	v_pk_fma_f32 v[0:1], v[10:11], v[0:1], v[12:13]
	s_nop 0
	v_cvt_pk_bf16_f32 v0, v0, v1
	v_cvt_pk_bf16_f32 v1, v2, v3
	global_store_dwordx2 v[28:29], v[0:1], off offset:1024
	global_load_dwordx4 v[0:3], v[22:23], off
	s_nop 0
	global_load_dwordx4 v[8:11], v[34:35], off offset:3072
	global_load_dwordx4 v[12:15], v[36:37], off offset:3072
	s_waitcnt vmcnt(2)
	v_pk_mul_f32 v[0:1], v[0:1], v[4:5]
	v_pk_mul_f32 v[2:3], v[2:3], v[6:7]
	s_waitcnt vmcnt(0)
	v_pk_add_f32 v[4:5], v[14:15], 1.0 op_sel_hi:[1,0]
	v_pk_add_f32 v[6:7], v[12:13], 1.0 op_sel_hi:[1,0]
	v_pk_fma_f32 v[2:3], v[2:3], v[4:5], v[10:11]
	v_pk_fma_f32 v[0:1], v[0:1], v[6:7], v[8:9]
	s_nop 0
	v_cvt_pk_bf16_f32 v0, v0, v1
	v_cvt_pk_bf16_f32 v1, v2, v3
	global_store_dwordx2 v[28:29], v[0:1], off offset:1536
	v_lshl_add_u64 v[28:29], v[28:29], 0, s[10:11]
	s_cbranch_scc0 .LBB0_1725

; __device__ __forceinline__ unsigned pk2(float lo, float hi) { f32x2_pk v = {lo, hi}; bf16x2_pk b = __builtin_convertvector(v, bf16x2_pk); return __builtin_bit_cast(unsigned, b); }
; __device__ __forceinline__ float wave_sum(float v) {
; #pragma unroll
;     for (int o = 1; o < 64; o <<= 1) v += __shfl_xor(v, o);
;     return v;
; }
; __device__ __forceinline__ void norm_phase(const float* xl, const float* xc, const float* g, const float* shift, const float* scale, bf16_t* Z, int row_lo, int nrows, int gw, int ngw, int lane) {
;     for (int m = row_lo + gw; m < nrows; m += ngw) {
;         const float* xr = m < ML ? xl + (size_t)m * D : xc + (size_t)(m - ML) * D; const int mr = m < ML ? (m >> 11) : 16;
;         f32x4 v[4]; float ss = 0.f;
; #pragma unroll
;         for (int j = 0; j < 4; ++j) { v[j] = *(const f32x4*)(xr + 4 * lane + 256 * j); ss += (v[j].x * v[j].x + v[j].y * v[j].y) + (v[j].z * v[j].z + v[j].w * v[j].w); }
;         const float ri = rsqrtf(wave_sum(ss) * (1.0f / D) + 1e-6f);
; #pragma unroll
;         for (int j = 0; j < 4; ++j) { const int c = 4 * lane + 256 * j; const f32x4 gv = *(const f32x4*)(g + c), sh = *(const f32x4*)(shift + (size_t)mr * 6144 + c), sc = *(const f32x4*)(scale + (size_t)mr * 6144 + c);
;             const f32x4 o = v[j] * ri * gv * (sc + 1.0f) + sh; u32x2 w; w.x = pk2(o.x, o.y); w.y = pk2(o.z, o.w); *(u32x2*)(Z + (size_t)m * D + c) = w; }
;     }
.LBB0_2005:
	global_load_dwordx4 v[12:15], v[26:27], off offset:-2048
	global_load_dwordx4 v[8:11], v[26:27], off offset:-1024
	s_addk_i32 s2, 0x600
	s_ashr_i32 s3, s2, 11
	s_cmpk_lt_i32 s2, 0x7a00
	s_waitcnt vmcnt(0)
	v_pk_mul_f32 v[0:1], v[14:15], v[14:15]
	v_pk_mul_f32 v[2:3], v[12:13], v[12:13]
	s_nop 0
	v_pk_mov_b32 v[4:5], v[2:3], v[0:1] op_sel:[1,0]
	v_mov_b32_e32 v3, v1
	v_pk_add_f32 v[30:31], v[4:5], v[2:3]
	v_pk_mul_f32 v[0:1], v[10:11], v[10:11]
	v_pk_mul_f32 v[2:3], v[8:9], v[8:9]
	v_pk_add_f32 v[30:31], v[30:31], v[30:31] op_sel:[0,1] op_sel_hi:[1,0]
	v_pk_mov_b32 v[4:5], v[2:3], v[0:1] op_sel:[1,0]
	v_mov_b32_e32 v3, v1
	v_pk_add_f32 v[32:33], v[4:5], v[2:3]
	global_load_dwordx4 v[0:3], v[26:27], off
	global_load_dwordx4 v[4:7], v[26:27], off offset:1024
	v_pk_add_f32 v[32:33], v[32:33], v[32:33] op_sel:[0,1] op_sel_hi:[1,0]
	v_lshl_add_u64 v[26:27], v[26:27], 0, s[60:61]
	s_waitcnt vmcnt(0)
	v_mul_f32_e32 v17, v4, v4
	v_mul_f32_e32 v28, v5, v5
	v_mov_b32_e32 v31, v17
	v_mov_b32_e32 v33, v28
	v_mul_f32_e32 v28, v1, v1
	v_pk_add_f32 v[30:31], v[30:31], v[32:33]
	v_pk_fma_f32 v[32:33], v[0:1], v[0:1], v[28:29] op_sel_hi:[1,1,0]
	v_mul_f32_e32 v28, v3, v3
	v_mul_f32_e32 v41, v6, v6
	v_mul_f32_e32 v44, v7, v7
	v_pk_fma_f32 v[42:43], v[2:3], v[2:3], v[28:29] op_sel_hi:[1,1,0]
	v_mov_b32_e32 v33, v41
	v_mov_b32_e32 v43, v44
	v_pk_add_f32 v[32:33], v[32:33], v[42:43]
	global_load_dwordx4 v[42:45], v[18:19], off
	v_pk_add_f32 v[30:31], v[30:31], v[32:33]
	v_mad_i64_i32 v[32:33], s[12:13], s3, v212, v[22:23]
	v_add_f32_e32 v17, v30, v31
	v_mad_i64_i32 v[30:31], s[12:13], s3, v212, v[20:21]
	global_load_dwordx4 v[46:49], v[30:31], off
	global_load_dwordx4 v[50:53], v[32:33], off
	s_nop 1
	v_add_f32_dpp v17, v17, v17 quad_perm:[1,0,3,2] row_mask:0xf bank_mask:0xf
	s_nop 1
	v_add_f32_dpp v17, v17, v17 quad_perm:[2,3,0,1] row_mask:0xf bank_mask:0xf
	s_nop 1
	v_add_f32_dpp v17, v17, v17 row_half_mirror row_mask:0xf bank_mask:0xf
	s_nop 1
	v_add_f32_dpp v17, v17, v17 row_mirror row_mask:0xf bank_mask:0xf
	v_mov_b32_e32 v28, v17
	s_nop 1
	v_permlane16_swap_b32_e32 v17, v28
	v_add_f32_e32 v17, v17, v28
	v_mov_b32_e32 v28, v17
	s_nop 1
	v_permlane32_swap_b32_e32 v17, v28
	v_add_f32_e32 v17, v17, v28
	s_waitcnt lgkmcnt(0)
	v_fmamk_f32 v17, v17, 0x3a800000, v199
	v_cmp_gt_f32_e32 vcc, s64, v17
	v_mul_f32_e32 v28, 0x4b800000, v17
	s_nop 0
	v_cndmask_b32_e32 v17, v17, v28, vcc
	v_rsq_f32_e32 v17, v17
	s_nop 0
	v_mul_f32_e32 v28, 0x45800000, v17
	v_cndmask_b32_e32 v28, v17, v28, vcc
	v_pk_mul_f32 v[14:15], v[14:15], v[28:29] op_sel_hi:[1,0]
	v_pk_mul_f32 v[12:13], v[12:13], v[28:29] op_sel_hi:[1,0]
	v_pk_mul_f32 v[10:11], v[10:11], v[28:29] op_sel_hi:[1,0]
	v_pk_mul_f32 v[8:9], v[8:9], v[28:29] op_sel_hi:[1,0]
	v_pk_mul_f32 v[2:3], v[2:3], v[28:29] op_sel_hi:[1,0]
	v_pk_mul_f32 v[0:1], v[0:1], v[28:29] op_sel_hi:[1,0]
	v_pk_mul_f32 v[6:7], v[6:7], v[28:29] op_sel_hi:[1,0]
	v_pk_mul_f32 v[4:5], v[4:5], v[28:29] op_sel_hi:[1,0]
	s_waitcnt vmcnt(2)
	v_pk_mul_f32 v[12:13], v[42:43], v[12:13]
	v_pk_mul_f32 v[14:15], v[44:45], v[14:15]
	s_waitcnt vmcnt(0)
	v_pk_add_f32 v[42:43], v[52:53], 1.0 op_sel_hi:[1,0]
	v_pk_add_f32 v[44:45], v[50:51], 1.0 op_sel_hi:[1,0]
	v_pk_fma_f32 v[14:15], v[42:43], v[14:15], v[48:49]
	v_pk_fma_f32 v[12:13], v[44:45], v[12:13], v[46:47]
	s_nop 0
	v_cvt_pk_bf16_f32 v12, v12, v13
	v_cvt_pk_bf16_f32 v13, v14, v15
	global_store_dwordx2 v[24:25], v[12:13], off
	global_load_dwordx4 v[12:15], v[18:19], off offset:1024
	s_nop 0
	global_load_dwordx4 v[42:45], v[30:31], off offset:1024
	global_load_dwordx4 v[46:49], v[32:33], off offset:1024
	s_waitcnt vmcnt(2)
	v_pk_mul_f32 v[8:9], v[12:13], v[8:9]
	v_pk_mul_f32 v[10:11], v[14:15], v[10:11]
	s_waitcnt vmcnt(0)
	v_pk_add_f32 v[12:13], v[48:49], 1.0 op_sel_hi:[1,0]
	v_pk_add_f32 v[14:15], v[46:47], 1.0 op_sel_hi:[1,0]
	v_pk_fma_f32 v[10:11], v[12:13], v[10:11], v[44:45]
	v_pk_fma_f32 v[8:9], v[14:15], v[8:9], v[42:43]
	s_nop 0
	v_cvt_pk_bf16_f32 v8, v8, v9
	v_cvt_pk_bf16_f32 v9, v10, v11
	global_store_dwordx2 v[24:25], v[8:9], off offset:512
	global_load_dwordx4 v[8:11], v[18:19], off offset:2048
	s_nop 0
	global_load_dwordx4 v[12:15], v[30:31], off offset:2048
	global_load_dwordx4 v[42:45], v[32:33], off offset:2048
	s_waitcnt vmcnt(2)
	v_pk_mul_f32 v[0:1], v[8:9], v[0:1]
	v_pk_mul_f32 v[2:3], v[10:11], v[2:3]
	s_waitcnt vmcnt(0)
	v_pk_add_f32 v[8:9], v[44:45], 1.0 op_sel_hi:[1,0]
	v_pk_add_f32 v[10:11], v[42:43], 1.0 op_sel_hi:[1,0]
	v_pk_fma_f32 v[2:3], v[8:9], v[2:3], v[14:15]
	v_pk_fma_f32 v[0:1], v[10:11], v[0:1], v[12:13]
	s_nop 0
	v_cvt_pk_bf16_f32 v0, v0, v1
	v_cvt_pk_bf16_f32 v1, v2, v3
	global_store_dwordx2 v[24:25], v[0:1], off offset:1024
	global_load_dwordx4 v[0:3], v[18:19], off offset:3072
	s_nop 0
	global_load_dwordx4 v[8:11], v[30:31], off offset:3072
	global_load_dwordx4 v[12:15], v[32:33], off offset:3072
	s_waitcnt vmcnt(2)
	v_pk_mul_f32 v[0:1], v[0:1], v[4:5]
	v_pk_mul_f32 v[2:3], v[2:3], v[6:7]
	s_waitcnt vmcnt(0)
	v_pk_add_f32 v[4:5], v[14:15], 1.0 op_sel_hi:[1,0]
	v_pk_add_f32 v[6:7], v[12:13], 1.0 op_sel_hi:[1,0]
	v_pk_fma_f32 v[2:3], v[2:3], v[4:5], v[10:11]
	v_pk_fma_f32 v[0:1], v[0:1], v[6:7], v[8:9]
	s_nop 0
	v_cvt_pk_bf16_f32 v0, v0, v1
	v_cvt_pk_bf16_f32 v1, v2, v3
	global_store_dwordx2 v[24:25], v[0:1], off offset:1536
	v_lshl_add_u64 v[24:25], v[24:25], 0, s[58:59]
	s_cbranch_scc1 .LBB0_2005

; __device__ __forceinline__ unsigned pk2(float lo, float hi) { f32x2_pk v = {lo, hi}; bf16x2_pk b = __builtin_convertvector(v, bf16x2_pk); return __builtin_bit_cast(unsigned, b); }
; __device__ __forceinline__ float wave_sum(float v) {
; #pragma unroll
;     for (int o = 1; o < 64; o <<= 1) v += __shfl_xor(v, o);
;     return v;
; }
; __device__ __forceinline__ void norm_phase(const float* xl, const float* xc, const float* g, const float* shift, const float* scale, bf16_t* Z, int row_lo, int nrows, int gw, int ngw, int lane) {
;     for (int m = row_lo + gw; m < nrows; m += ngw) {
;         const float* xr = m < ML ? xl + (size_t)m * D : xc + (size_t)(m - ML) * D; const int mr = m < ML ? (m >> 11) : 16;
;         f32x4 v[4]; float ss = 0.f;
; #pragma unroll
;         for (int j = 0; j < 4; ++j) { v[j] = *(const f32x4*)(xr + 4 * lane + 256 * j); ss += (v[j].x * v[j].x + v[j].y * v[j].y) + (v[j].z * v[j].z + v[j].w * v[j].w); }
;         const float ri = rsqrtf(wave_sum(ss) * (1.0f / D) + 1e-6f);
; #pragma unroll
;         for (int j = 0; j < 4; ++j) { const int c = 4 * lane + 256 * j; const f32x4 gv = *(const f32x4*)(g + c), sh = *(const f32x4*)(shift + (size_t)mr * 6144 + c), sc = *(const f32x4*)(scale + (size_t)mr * 6144 + c);
;             const f32x4 o = v[j] * ri * gv * (sc + 1.0f) + sh; u32x2 w; w.x = pk2(o.x, o.y); w.y = pk2(o.z, o.w); *(u32x2*)(Z + (size_t)m * D + c) = w; }
;     }
.LBB0_2115:
	global_load_dwordx4 v[12:15], v35, s[12:13]
	global_load_dwordx4 v[8:11], v35, s[12:13] offset:1024
	s_min_i32 s3, s14, 0x8000
	s_ashr_i32 s3, s3, 11
	s_lshl_b64 s[10:11], s[10:11], 11
	s_add_i32 s86, s86, s80
	s_waitcnt vmcnt(0)
	v_pk_mul_f32 v[0:1], v[14:15], v[14:15]
	v_pk_mul_f32 v[2:3], v[12:13], v[12:13]
	s_nop 0
	v_pk_mov_b32 v[4:5], v[2:3], v[0:1] op_sel:[1,0]
	v_mov_b32_e32 v3, v1
	v_pk_add_f32 v[26:27], v[4:5], v[2:3]
	v_pk_mul_f32 v[0:1], v[10:11], v[10:11]
	v_pk_mul_f32 v[2:3], v[8:9], v[8:9]
	v_pk_add_f32 v[26:27], v[26:27], v[26:27] op_sel:[0,1] op_sel_hi:[1,0]
	v_pk_mov_b32 v[4:5], v[2:3], v[0:1] op_sel:[1,0]
	v_mov_b32_e32 v3, v1
	v_pk_add_f32 v[28:29], v[4:5], v[2:3]
	global_load_dwordx4 v[0:3], v35, s[12:13] offset:2048
	global_load_dwordx4 v[4:7], v35, s[12:13] offset:3072
	v_pk_add_f32 v[28:29], v[28:29], v[28:29] op_sel:[0,1] op_sel_hi:[1,0]
	s_waitcnt vmcnt(0)
	v_mul_f32_e32 v24, v4, v4
	v_mul_f32_e32 v36, v5, v5
	v_mov_b32_e32 v27, v24
	v_mov_b32_e32 v29, v36
	v_mul_f32_e32 v24, v1, v1
	v_mul_f32_e32 v37, v6, v6
	v_pk_add_f32 v[26:27], v[26:27], v[28:29]
	v_pk_fma_f32 v[28:29], v[0:1], v[0:1], v[24:25] op_sel_hi:[1,1,0]
	v_mul_f32_e32 v24, v3, v3
	v_mul_f32_e32 v38, v7, v7
	v_mov_b32_e32 v29, v37
	v_pk_fma_f32 v[36:37], v[2:3], v[2:3], v[24:25] op_sel_hi:[1,1,0]
	s_nop 0
	v_mov_b32_e32 v37, v38
	v_pk_add_f32 v[28:29], v[28:29], v[36:37]
	global_load_dwordx4 v[36:39], v[16:17], off
	v_pk_add_f32 v[26:27], v[26:27], v[28:29]
	v_mad_i64_i32 v[28:29], s[12:13], s3, v212, v[20:21]
	v_add_f32_e32 v24, v26, v27
	global_load_dwordx4 v[44:47], v[28:29], off
	s_nop 1
	v_add_f32_dpp v24, v24, v24 quad_perm:[1,0,3,2] row_mask:0xf bank_mask:0xf
	s_nop 1
	v_add_f32_dpp v24, v24, v24 quad_perm:[2,3,0,1] row_mask:0xf bank_mask:0xf
	s_nop 1
	v_add_f32_dpp v24, v24, v24 row_half_mirror row_mask:0xf bank_mask:0xf
	s_nop 1
	v_add_f32_dpp v24, v24, v24 row_mirror row_mask:0xf bank_mask:0xf
	v_mov_b32_e32 v26, v24
	s_nop 1
	v_permlane16_swap_b32_e32 v24, v26
	v_add_f32_e32 v24, v24, v26
	v_mov_b32_e32 v26, v24
	s_nop 1
	v_permlane32_swap_b32_e32 v24, v26
	v_add_f32_e32 v24, v24, v26
	s_waitcnt lgkmcnt(0)
	v_fmamk_f32 v24, v24, 0x3a800000, v199
	v_cmp_gt_f32_e32 vcc, s64, v24
	v_mul_f32_e32 v26, 0x4b800000, v24
	s_nop 0
	v_cndmask_b32_e32 v24, v24, v26, vcc
	v_rsq_f32_e32 v24, v24
	s_nop 0
	v_mul_f32_e32 v26, 0x45800000, v24
	v_cndmask_b32_e32 v24, v24, v26, vcc
	v_mad_i64_i32 v[26:27], s[12:13], s3, v212, v[18:19]
	global_load_dwordx4 v[40:43], v[26:27], off
	v_pk_mul_f32 v[14:15], v[14:15], v[24:25] op_sel_hi:[1,0]
	v_pk_mul_f32 v[12:13], v[12:13], v[24:25] op_sel_hi:[1,0]
	v_pk_mul_f32 v[10:11], v[10:11], v[24:25] op_sel_hi:[1,0]
	v_pk_mul_f32 v[8:9], v[8:9], v[24:25] op_sel_hi:[1,0]
	v_pk_mul_f32 v[2:3], v[2:3], v[24:25] op_sel_hi:[1,0]
	v_pk_mul_f32 v[0:1], v[0:1], v[24:25] op_sel_hi:[1,0]
	s_add_i32 s3, s86, 0x8000
	s_add_u32 s6, s6, s80
	v_pk_mul_f32 v[6:7], v[6:7], v[24:25] op_sel_hi:[1,0]
	v_pk_mul_f32 v[4:5], v[4:5], v[24:25] op_sel_hi:[1,0]
	s_addc_u32 s7, s7, s81
	s_add_u32 s8, s8, s48
	s_addc_u32 s9, s9, s49
	s_cmp_lt_i32 s3, 0x9000
	s_waitcnt vmcnt(2)
	v_pk_mul_f32 v[12:13], v[36:37], v[12:13]
	v_pk_mul_f32 v[14:15], v[38:39], v[14:15]
	s_waitcnt vmcnt(1)
	v_pk_add_f32 v[36:37], v[46:47], 1.0 op_sel_hi:[1,0]
	v_pk_add_f32 v[38:39], v[44:45], 1.0 op_sel_hi:[1,0]
	v_lshl_add_u64 v[44:45], v[22:23], 0, s[10:11]
	s_waitcnt vmcnt(0)
	v_pk_fma_f32 v[14:15], v[36:37], v[14:15], v[42:43]
	v_pk_fma_f32 v[12:13], v[38:39], v[12:13], v[40:41]
	s_nop 0
	v_cvt_pk_bf16_f32 v12, v12, v13
	v_cvt_pk_bf16_f32 v13, v14, v15
	global_store_dwordx2 v[44:45], v[12:13], off
	global_load_dwordx4 v[12:15], v[16:17], off offset:1024
	s_nop 0
	global_load_dwordx4 v[36:39], v[26:27], off offset:1024
	global_load_dwordx4 v[40:43], v[28:29], off offset:1024
	s_waitcnt vmcnt(2)
	v_pk_mul_f32 v[8:9], v[12:13], v[8:9]
	v_pk_mul_f32 v[10:11], v[14:15], v[10:11]
	s_waitcnt vmcnt(0)
	v_pk_add_f32 v[12:13], v[42:43], 1.0 op_sel_hi:[1,0]
	v_pk_add_f32 v[14:15], v[40:41], 1.0 op_sel_hi:[1,0]
	v_pk_fma_f32 v[10:11], v[12:13], v[10:11], v[38:39]
	v_pk_fma_f32 v[8:9], v[14:15], v[8:9], v[36:37]
	s_nop 0
	v_cvt_pk_bf16_f32 v8, v8, v9
	v_cvt_pk_bf16_f32 v9, v10, v11
	global_store_dwordx2 v[44:45], v[8:9], off offset:512
	global_load_dwordx4 v[8:11], v[16:17], off offset:2048
	s_nop 0
	global_load_dwordx4 v[12:15], v[26:27], off offset:2048
	global_load_dwordx4 v[36:39], v[28:29], off offset:2048
	s_waitcnt vmcnt(2)
	v_pk_mul_f32 v[0:1], v[8:9], v[0:1]
	v_pk_mul_f32 v[2:3], v[10:11], v[2:3]
	s_waitcnt vmcnt(0)
	v_pk_add_f32 v[8:9], v[38:39], 1.0 op_sel_hi:[1,0]
	v_pk_add_f32 v[10:11], v[36:37], 1.0 op_sel_hi:[1,0]
	v_pk_fma_f32 v[2:3], v[8:9], v[2:3], v[14:15]
	v_pk_fma_f32 v[0:1], v[10:11], v[0:1], v[12:13]
	s_nop 0
	v_cvt_pk_bf16_f32 v0, v0, v1
	v_cvt_pk_bf16_f32 v1, v2, v3
	global_store_dwordx2 v[44:45], v[0:1], off offset:1024
	global_load_dwordx4 v[0:3], v[16:17], off offset:3072
	s_nop 0
	global_load_dwordx4 v[8:11], v[26:27], off offset:3072
	global_load_dwordx4 v[12:15], v[28:29], off offset:3072
	s_waitcnt vmcnt(2)
	v_pk_mul_f32 v[0:1], v[0:1], v[4:5]
	v_pk_mul_f32 v[2:3], v[2:3], v[6:7]
	s_waitcnt vmcnt(0)
	v_pk_add_f32 v[4:5], v[14:15], 1.0 op_sel_hi:[1,0]
	v_pk_add_f32 v[6:7], v[12:13], 1.0 op_sel_hi:[1,0]
	v_pk_fma_f32 v[2:3], v[2:3], v[4:5], v[10:11]
	v_pk_fma_f32 v[0:1], v[0:1], v[6:7], v[8:9]
	s_nop 0
	v_cvt_pk_bf16_f32 v0, v0, v1
	v_cvt_pk_bf16_f32 v1, v2, v3
	global_store_dwordx2 v[44:45], v[0:1], off offset:1536
	s_cbranch_scc0 .LBB0_2118

; __device__ __forceinline__ float wave_sum(float v) {
; #pragma unroll
;     for (int o = 1; o < 64; o <<= 1) v += __shfl_xor(v, o);
;     return v;
; }
; __device__ __forceinline__ void final_norm_phase(float* x, const float* g, int gw, int ngw, int lane) {
;     for (int m = gw; m < ML; m += ngw) { float* xr = x + (size_t)m * D; f32x4 v[4]; float ss = 0.f;
; #pragma unroll
;         for (int j = 0; j < 4; ++j) { v[j] = *(const f32x4*)(xr + 4 * lane + 256 * j); ss += (v[j].x * v[j].x + v[j].y * v[j].y) + (v[j].z * v[j].z + v[j].w * v[j].w); }
;         const float ri = rsqrtf(wave_sum(ss) * (1.0f / D) + 1e-6f);
; #pragma unroll
;         for (int j = 0; j < 4; ++j) { const int c = 4 * lane + 256 * j; *(f32x4*)(xr + c) = v[j] * ri * *(const f32x4*)(g + c); } }
.LBB0_2184:
	global_load_dwordx4 v[12:15], v[2:3], off offset:-2048
	global_load_dwordx4 v[16:19], v[2:3], off offset:-1024
	global_load_dwordx4 v[20:23], v[2:3], off offset:1024
	global_load_dwordx4 v[24:27], v[2:3], off
	global_load_dwordx4 v[28:31], v[0:1], off
	s_add_i32 s2, s2, s80
	s_cmp_lt_i32 s2, 0x8000
	s_waitcnt vmcnt(0)
	v_pk_mul_f32 v[32:33], v[14:15], v[14:15]
	v_pk_mul_f32 v[34:35], v[12:13], v[12:13]
	v_pk_mul_f32 v[36:37], v[18:19], v[18:19]
	v_pk_mul_f32 v[38:39], v[16:17], v[16:17]
	v_pk_mov_b32 v[44:45], v[34:35], v[32:33] op_sel:[1,0]
	v_mov_b32_e32 v35, v33
	v_pk_mov_b32 v[32:33], v[38:39], v[36:37] op_sel:[1,0]
	v_mov_b32_e32 v39, v37
	v_mul_f32_e32 v43, v21, v21
	v_mul_f32_e32 v40, v25, v25
	v_mul_f32_e32 v42, v27, v27
	v_pk_add_f32 v[34:35], v[44:45], v[34:35]
	v_pk_add_f32 v[32:33], v[32:33], v[38:39]
	v_mul_f32_e32 v11, v20, v20
	v_mul_f32_e32 v46, v22, v22
	v_mul_f32_e32 v47, v23, v23
	v_pk_fma_f32 v[36:37], v[24:25], v[24:25], v[40:41] op_sel_hi:[1,1,0]
	v_pk_fma_f32 v[40:41], v[26:27], v[26:27], v[42:43] op_sel_hi:[1,1,0]
	v_pk_add_f32 v[34:35], v[34:35], v[34:35] op_sel:[0,1] op_sel_hi:[1,0]
	v_pk_add_f32 v[32:33], v[32:33], v[32:33] op_sel:[0,1] op_sel_hi:[1,0]
	v_mov_b32_e32 v37, v46
	v_mov_b32_e32 v41, v47
	v_mov_b32_e32 v35, v11
	v_mov_b32_e32 v33, v43
	v_pk_add_f32 v[36:37], v[36:37], v[40:41]
	v_pk_add_f32 v[32:33], v[34:35], v[32:33]
	s_nop 0
	v_pk_add_f32 v[32:33], v[32:33], v[36:37]
	s_nop 0
	v_add_f32_e32 v11, v32, v33
	s_nop 1
	v_add_f32_dpp v11, v11, v11 quad_perm:[1,0,3,2] row_mask:0xf bank_mask:0xf
	s_nop 1
	v_add_f32_dpp v11, v11, v11 quad_perm:[2,3,0,1] row_mask:0xf bank_mask:0xf
	s_nop 1
	v_add_f32_dpp v11, v11, v11 row_half_mirror row_mask:0xf bank_mask:0xf
	s_nop 1
	v_add_f32_dpp v11, v11, v11 row_mirror row_mask:0xf bank_mask:0xf
	v_mov_b32_e32 v32, v11
	s_nop 1
	v_permlane16_swap_b32_e32 v11, v32
	v_add_f32_e32 v11, v11, v32
	v_mov_b32_e32 v32, v11
	s_nop 1
	v_permlane32_swap_b32_e32 v11, v32
	v_add_f32_e32 v11, v11, v32
	s_waitcnt lgkmcnt(0)
	v_fmamk_f32 v11, v11, 0x3a800000, v10
	v_mul_f32_e32 v32, 0x4b800000, v11
	v_cmp_gt_f32_e32 vcc, s0, v11
	s_nop 1
	v_cndmask_b32_e32 v11, v11, v32, vcc
	v_rsq_f32_e32 v11, v11
	s_nop 0
	v_mul_f32_e32 v32, 0x45800000, v11
	v_cndmask_b32_e32 v32, v11, v32, vcc
	v_pk_mul_f32 v[12:13], v[12:13], v[32:33] op_sel_hi:[1,0]
	v_pk_mul_f32 v[14:15], v[14:15], v[32:33] op_sel_hi:[1,0]
	v_pk_mul_f32 v[12:13], v[28:29], v[12:13]
	v_pk_mul_f32 v[14:15], v[30:31], v[14:15]
	global_store_dwordx4 v[2:3], v[12:15], off offset:-2048
	global_load_dwordx4 v[12:15], v[0:1], off offset:1024
	v_pk_mul_f32 v[18:19], v[18:19], v[32:33] op_sel_hi:[1,0]
	v_pk_mul_f32 v[16:17], v[16:17], v[32:33] op_sel_hi:[1,0]
	s_waitcnt vmcnt(0)
	v_pk_mul_f32 v[14:15], v[14:15], v[18:19]
	v_pk_mul_f32 v[12:13], v[12:13], v[16:17]
	global_store_dwordx4 v[2:3], v[12:15], off offset:-1024
	global_load_dwordx4 v[12:15], v[0:1], off offset:2048
	v_pk_mul_f32 v[16:17], v[26:27], v[32:33] op_sel_hi:[1,0]
	v_pk_mul_f32 v[18:19], v[24:25], v[32:33] op_sel_hi:[1,0]
	s_waitcnt vmcnt(0)
	v_pk_mul_f32 v[14:15], v[14:15], v[16:17]
	v_pk_mul_f32 v[12:13], v[12:13], v[18:19]
	global_store_dwordx4 v[2:3], v[12:15], off
	global_load_dwordx4 v[12:15], v[0:1], off offset:3072
	v_pk_mul_f32 v[16:17], v[22:23], v[32:33] op_sel_hi:[1,0]
	v_pk_mul_f32 v[18:19], v[20:21], v[32:33] op_sel_hi:[1,0]
	s_waitcnt vmcnt(0)
	v_pk_mul_f32 v[14:15], v[14:15], v[16:17]
	v_pk_mul_f32 v[12:13], v[12:13], v[18:19]
	global_store_dwordx4 v[2:3], v[12:15], off offset:1024
	v_lshl_add_u64 v[2:3], v[2:3], 0, s[48:49]
	s_cbranch_scc1 .LBB0_2184
